# WKV scan: prep waves also write a pair-swapped V copy to LDS; recurrence lanes fetch their V row pair with one ds_read_b64 instead of two ds_read_b32
# speedup vs baseline: 1.0097x; 1.0097x over previous
.LBB0_540:
	s_lshl_b32 s51, s88, 7
	s_and_b32 s20, s51, 0xfffff000
	v_or_b32_e32 v2, s20, v59
	v_ashrrev_i32_e32 v3, 31, v2
	s_lshl_b32 s50, s4, 6
	v_lshlrev_b64 v[104:105], 10, v[2:3]
	v_or_b32_e32 v17, s50, v104
	s_andn2_b64 vcc, exec, s[2:3]
	v_or_b32_e32 v104, v17, v60
	s_cbranch_vccnz .LBB0_544
	v_lshlrev_b64 v[16:17], 1, v[104:105]
	v_lshl_add_u64 v[18:19], s[24:25], 0, v[16:17]
	v_lshl_add_u64 v[20:21], s[26:27], 0, v[16:17]
	global_load_dwordx2 v[18:19], v[18:19], off
	v_lshl_add_u64 v[22:23], s[28:29], 0, v[16:17]
	global_load_dwordx2 v[20:21], v[20:21], off
	v_lshl_add_u64 v[24:25], s[30:31], 0, v[16:17]
	v_lshl_add_u64 v[16:17], s[34:35], 0, v[16:17]
	global_load_dwordx2 v[22:23], v[22:23], off
	v_cmp_eq_u32_e32 vcc, 0, v0
	global_load_dwordx2 v[24:25], v[24:25], off
	s_waitcnt vmcnt(0)
	v_lshlrev_b32_e32 v28, 16, v20
	global_load_dwordx2 v[26:27], v[16:17], off
	v_and_b32_e32 v29, 0xffff0000, v20
	v_lshlrev_b32_e32 v30, 16, v21
	v_and_b32_e32 v31, 0xffff0000, v21
	v_lshlrev_b32_e32 v40, 16, v24
	v_and_b32_e32 v41, 0xffff0000, v24
	v_lshlrev_b32_e32 v42, 16, v25
	v_and_b32_e32 v43, 0xffff0000, v25
	v_pk_mul_f32 v[36:37], v[4:5], v[28:29]
	v_pk_mul_f32 v[38:39], v[6:7], v[30:31]
	v_lshlrev_b32_e32 v16, 16, v18
	v_and_b32_e32 v17, 0xffff0000, v18
	v_lshlrev_b32_e32 v18, 16, v19
	v_and_b32_e32 v19, 0xffff0000, v19
	v_lshlrev_b32_e32 v20, 16, v22
	v_and_b32_e32 v21, 0xffff0000, v22
	v_mul_f32_e32 v46, 0xbfb8aa3b, v40
	v_mul_f32_e32 v47, 0xbfb8aa3b, v41
	v_mul_f32_e32 v48, 0xbfb8aa3b, v42
	v_mul_f32_e32 v49, 0xbfb8aa3b, v43
	v_pk_mul_f32 v[40:41], v[38:39], v[38:39]
	v_pk_mul_f32 v[42:43], v[36:37], v[36:37]
	v_lshlrev_b32_e32 v22, 16, v23
	v_and_b32_e32 v23, 0xffff0000, v23
	ds_write_b128 v69, v[16:19]
	ds_write_b128 v69, v[20:23] offset:12288
	v_add_u32_e32 v197, 0x1d000, v69
	ds_write2_b32 v197, v21, v20 offset1:1
	ds_write2_b32 v197, v23, v22 offset0:2 offset1:3
	v_exp_f32_e32 v20, v46
	v_exp_f32_e32 v21, v47
	v_pk_mov_b32 v[46:47], v[42:43], v[40:41] op_sel:[1,0]
	v_mov_b32_e32 v43, v41
	v_exp_f32_e32 v22, v48
	v_exp_f32_e32 v23, v49
	ds_write_b128 v69, v[20:23] offset:4096
	s_waitcnt vmcnt(0)
	v_lshlrev_b32_e32 v32, 16, v26
	v_and_b32_e32 v33, 0xffff0000, v26
	v_lshlrev_b32_e32 v34, 16, v27
	v_and_b32_e32 v35, 0xffff0000, v27
	v_pk_add_f32 v[24:25], v[34:35], -1.0 op_sel_hi:[1,0]
	v_pk_add_f32 v[26:27], v[32:33], -1.0 op_sel_hi:[1,0]
	v_pk_fma_f32 v[24:25], v[10:11], v[24:25], 1.0 op_sel_hi:[1,1,0]
	v_pk_fma_f32 v[44:45], v[8:9], v[26:27], 1.0 op_sel_hi:[1,1,0]
	v_pk_mul_f32 v[26:27], v[24:25], v[30:31]
	v_pk_mul_f32 v[24:25], v[44:45], v[28:29]
	v_pk_add_f32 v[28:29], v[46:47], v[42:43]
	v_pk_mul_f32 v[16:17], v[24:25], v[16:17]
	v_pk_mul_f32 v[18:19], v[26:27], v[18:19]
	ds_write_b128 v69, v[24:27] offset:8192
	v_add_f32_e32 v24, v28, v29
	v_pk_mul_f32 v[18:19], v[14:15], v[18:19]
	v_pk_mul_f32 v[16:17], v[12:13], v[16:17]
	v_add_f32_dpp v24, v24, v24 quad_perm:[1,0,3,2] row_mask:0xf bank_mask:0xf bound_ctrl:1
	v_add_f32_e32 v16, v16, v17
	v_add_f32_e32 v17, v18, v19
	v_add_f32_dpp v18, v24, v24 quad_perm:[2,3,0,1] row_mask:0xf bank_mask:0xf bound_ctrl:1
	v_add_f32_e32 v16, v16, v17
	s_nop 0
	v_add_f32_dpp v17, v18, v18 row_half_mirror row_mask:0xf bank_mask:0xf bound_ctrl:1
	v_add_f32_dpp v16, v16, v16 quad_perm:[1,0,3,2] row_mask:0xf bank_mask:0xf bound_ctrl:1
	s_nop 0
	v_add_f32_dpp v17, v17, v17 row_mirror row_mask:0xf bank_mask:0xf bound_ctrl:1
	v_max_f32_e32 v17, 0x179abe15, v17
	v_rsq_f32_e32 v18, v17
	v_add_f32_dpp v16, v16, v16 quad_perm:[2,3,0,1] row_mask:0xf bank_mask:0xf bound_ctrl:1
	v_pk_mul_f32 v[20:21], v[38:39], v[18:19] op_sel_hi:[1,0]
	s_nop 0
	v_add_f32_dpp v16, v16, v16 row_half_mirror row_mask:0xf bank_mask:0xf bound_ctrl:1
	v_pk_mul_f32 v[18:19], v[36:37], v[18:19] op_sel_hi:[1,0]
	ds_write_b128 v69, v[18:21] offset:16384
	v_mov_b32_dpp v17, v16 row_mirror row_mask:0xf bank_mask:0xf bound_ctrl:1
	v_pk_mul_f32 v[20:21], v[20:21], v[34:35]
	v_pk_mul_f32 v[18:19], v[18:19], v[32:33]
	ds_write_b128 v69, v[18:21] offset:20480
	s_and_saveexec_b64 s[2:3], vcc
	s_cbranch_execz .LBB0_543
	v_lshlrev_b64 v[2:3], 6, v[2:3]
	v_lshl_add_u64 v[2:3], s[38:39], 0, v[2:3]
	s_lshl_b32 s40, s4, 2
	v_lshl_add_u64 v[2:3], v[2:3], 0, s[40:41]
	v_add_f32_e32 v16, v16, v17
	global_store_dword v[2:3], v16, off

.LBB0_544:
	s_and_b32 s2, s65, 0xfffff000
	s_lshl_b32 s50, s50, 1
	v_add_u32_e32 v141, s2, v123
	v_or_b32_e32 v142, s2, v139
	s_add_u32 s2, s36, s50
	s_addc_u32 s3, s37, 0
	s_lshl_b32 s90, s5, 5
	s_lshl_b32 s5, s5, 6
	s_add_u32 s2, s2, s5
	s_addc_u32 s3, s3, 0
	v_mov_b32_e32 v93, v1
	s_lshl_b32 s4, s4, 2
	v_mov_b32_e32 v2, v1
	v_mov_b32_e32 v3, v1
	v_lshl_add_u64 v[106:107], s[2:3], 0, v[92:93]
	v_cmp_eq_u32_e64 s[2:3], 0, v16
	s_add_u32 s52, s38, s4
	v_mov_b32_e32 v0, v1
	v_mov_b64_e32 v[18:19], v[2:3]
	v_mov_b64_e32 v[22:23], v[2:3]
	s_mov_b32 s91, 0
	s_addc_u32 s53, s39, 0
	v_mov_b64_e32 v[16:17], v[0:1]
	v_mov_b64_e32 v[20:21], v[0:1]
	s_mov_b32 s89, s60
	s_mov_b32 s92, 0
	v_mbcnt_lo_u32_b32 v190, -1, 0
	v_mbcnt_hi_u32_b32 v190, -1, v190
	v_and_b32_e32 v191, 15, v190
	v_lshrrev_b32_e32 v192, 4, v190
	v_and_b32_e32 v193, 1, v190
	v_lshl_add_u32 v192, v192, 1, v193
	v_lshlrev_b32_e32 v194, 4, v191
	s_lshl_b32 s4, s90, 2
	s_add_i32 s4, s4, s59
	v_lshl_add_u32 v195, v192, 2, s4
	v_mul_u32_u24_e32 v193, 0x19ffc, v193
	v_add_u32_e32 v195, v195, v193
	v_lshrrev_b32_e32 v191, 1, v191
	v_lshlrev_b32_e32 v191, 2, v191
	s_lshl_b32 s4, s59, 3
	v_lshl_add_u32 v196, v192, 5, v191
	v_add_u32_e32 v196, s4, v196
	s_waitcnt vmcnt(0) lgkmcnt(0)
	s_barrier
	s_branch .LBB0_547
.LBB0_545:
	s_mul_i32 s4, s93, 0x6000
	s_lshl_b32 s5, s93, 14
	v_add_u32_e32 v2, s4, v194
	v_add_u32_e32 v3, s4, v195
	v_add_u32_e32 v0, s5, v196
	ds_read_b128 v[24:27], v2 offset:16384
	ds_read_b64 v[44:45], v3 offset:12288
	ds_read_b128 v[36:39], v2 offset:8192
	ds_read_b128 v[28:31], v2 offset:4096
	ds_read_b128 v[32:35], v2 offset:20480
	ds_read_b128 v[40:43], v2 offset:0
	ds_read_b128 v[144:147], v2 offset:16640
	ds_read_b64 v[164:165], v3 offset:12544
	ds_read_b128 v[156:159], v2 offset:8448
	ds_read_b128 v[148:151], v2 offset:4352
	ds_read_b128 v[152:155], v2 offset:20736
	s_waitcnt lgkmcnt(5)
	v_pk_mul_f32 v[46:47], v[16:17], v[24:25] op_sel_hi:[1,0]
	v_pk_fma_f32 v[46:47], v[18:19], v[24:25], v[46:47] op_sel:[0,1,0] op_sel_hi:[1,1,1]
	v_pk_fma_f32 v[46:47], v[20:21], v[26:27], v[46:47] op_sel_hi:[1,0,1]
	v_pk_fma_f32 v[46:47], v[22:23], v[26:27], v[46:47] op_sel:[0,1,0] op_sel_hi:[1,1,1]
	ds_read_b128 v[160:163], v2 offset:256
	v_pk_mul_f32 v[168:169], v[44:45], v[36:37] op_sel_hi:[1,0]
	v_add_f32_dpp v48, v47, v46 quad_perm:[1,0,3,2] row_mask:0xf bank_mask:0xf bound_ctrl:1
	v_pk_mul_f32 v[170:171], v[44:45], v[36:37] op_sel:[0,1] op_sel_hi:[1,1]
	s_nop 0
	v_add_f32_dpp v48, v48, v48 quad_perm:[2,3,0,1] row_mask:0xf bank_mask:0xf bound_ctrl:1
	v_pk_mul_f32 v[172:173], v[44:45], v[38:39] op_sel_hi:[1,0]
	v_pk_mul_f32 v[174:175], v[44:45], v[38:39] op_sel:[0,1] op_sel_hi:[1,1]
	v_add_f32_dpp v48, v48, v48 row_ror:4 row_mask:0xf bank_mask:0xf bound_ctrl:1
	v_pk_fma_f32 v[168:169], v[16:17], v[28:29], v[168:169] op_sel_hi:[1,0,1]
	v_pk_fma_f32 v[170:171], v[18:19], v[28:29], v[170:171] op_sel:[0,1,0] op_sel_hi:[1,1,1]
	v_add_f32_dpp v48, v48, v48 row_ror:8 row_mask:0xf bank_mask:0xf bound_ctrl:1
	v_pk_fma_f32 v[172:173], v[20:21], v[30:31], v[172:173] op_sel_hi:[1,0,1]
	v_pk_fma_f32 v[174:175], v[22:23], v[30:31], v[174:175] op_sel:[0,1,0] op_sel_hi:[1,1,1]
	v_mov_b32_dpp v49, v48 quad_perm:[1,0,3,2] row_mask:0xf bank_mask:0xf bound_ctrl:1
	v_pk_fma_f32 v[16:17], v[48:49], v[32:33], v[168:169] op_sel_hi:[1,0,1] neg_lo:[0,1,0] neg_hi:[0,1,0]
	v_pk_fma_f32 v[18:19], v[48:49], v[32:33], v[170:171] op_sel:[0,1,0] op_sel_hi:[1,1,1] neg_lo:[0,1,0] neg_hi:[0,1,0]
	v_pk_fma_f32 v[20:21], v[48:49], v[34:35], v[172:173] op_sel_hi:[1,0,1] neg_lo:[0,1,0] neg_hi:[0,1,0]
	v_pk_fma_f32 v[22:23], v[48:49], v[34:35], v[174:175] op_sel:[0,1,0] op_sel_hi:[1,1,1] neg_lo:[0,1,0] neg_hi:[0,1,0]
	ds_read_b128 v[24:27], v2 offset:16896
	ds_read_b64 v[44:45], v3 offset:12800
	ds_read_b128 v[36:39], v2 offset:8704
	ds_read_b128 v[28:31], v2 offset:4608
	ds_read_b128 v[32:35], v2 offset:20992
	s_waitcnt lgkmcnt(5)
	v_pk_mul_f32 v[46:47], v[16:17], v[144:145] op_sel_hi:[1,0]
	v_pk_mul_f32 v[50:51], v[16:17], v[40:41] op_sel_hi:[1,0]
	v_pk_fma_f32 v[46:47], v[18:19], v[144:145], v[46:47] op_sel:[0,1,0] op_sel_hi:[1,1,1]
	v_pk_fma_f32 v[50:51], v[18:19], v[40:41], v[50:51] op_sel:[0,1,0] op_sel_hi:[1,1,1]
	v_pk_fma_f32 v[46:47], v[20:21], v[146:147], v[46:47] op_sel_hi:[1,0,1]
	v_pk_fma_f32 v[50:51], v[20:21], v[42:43], v[50:51] op_sel_hi:[1,0,1]
	v_pk_fma_f32 v[46:47], v[22:23], v[146:147], v[46:47] op_sel:[0,1,0] op_sel_hi:[1,1,1]
	v_pk_fma_f32 v[50:51], v[22:23], v[42:43], v[50:51] op_sel:[0,1,0] op_sel_hi:[1,1,1]
	ds_read_b128 v[40:43], v2 offset:512
	v_pk_mul_f32 v[168:169], v[164:165], v[156:157] op_sel_hi:[1,0]
	v_add_f32_dpp v48, v47, v46 quad_perm:[1,0,3,2] row_mask:0xf bank_mask:0xf bound_ctrl:1
	v_add_f32_dpp v52, v51, v50 quad_perm:[1,0,3,2] row_mask:0xf bank_mask:0xf bound_ctrl:1
	v_pk_mul_f32 v[170:171], v[164:165], v[156:157] op_sel:[0,1] op_sel_hi:[1,1]
	v_add_f32_dpp v48, v48, v48 quad_perm:[2,3,0,1] row_mask:0xf bank_mask:0xf bound_ctrl:1
	ds_write_b32 v0, v52 offset:49152
	v_pk_mul_f32 v[172:173], v[164:165], v[158:159] op_sel_hi:[1,0]
	v_pk_mul_f32 v[174:175], v[164:165], v[158:159] op_sel:[0,1] op_sel_hi:[1,1]
	v_add_f32_dpp v48, v48, v48 row_ror:4 row_mask:0xf bank_mask:0xf bound_ctrl:1
	v_pk_fma_f32 v[168:169], v[16:17], v[148:149], v[168:169] op_sel_hi:[1,0,1]
	v_pk_fma_f32 v[170:171], v[18:19], v[148:149], v[170:171] op_sel:[0,1,0] op_sel_hi:[1,1,1]
	v_add_f32_dpp v48, v48, v48 row_ror:8 row_mask:0xf bank_mask:0xf bound_ctrl:1
	v_pk_fma_f32 v[172:173], v[20:21], v[150:151], v[172:173] op_sel_hi:[1,0,1]
	v_pk_fma_f32 v[174:175], v[22:23], v[150:151], v[174:175] op_sel:[0,1,0] op_sel_hi:[1,1,1]
	v_mov_b32_dpp v49, v48 quad_perm:[1,0,3,2] row_mask:0xf bank_mask:0xf bound_ctrl:1
	v_pk_fma_f32 v[16:17], v[48:49], v[152:153], v[168:169] op_sel_hi:[1,0,1] neg_lo:[0,1,0] neg_hi:[0,1,0]
	v_pk_fma_f32 v[18:19], v[48:49], v[152:153], v[170:171] op_sel:[0,1,0] op_sel_hi:[1,1,1] neg_lo:[0,1,0] neg_hi:[0,1,0]
	v_pk_fma_f32 v[20:21], v[48:49], v[154:155], v[172:173] op_sel_hi:[1,0,1] neg_lo:[0,1,0] neg_hi:[0,1,0]
	v_pk_fma_f32 v[22:23], v[48:49], v[154:155], v[174:175] op_sel:[0,1,0] op_sel_hi:[1,1,1] neg_lo:[0,1,0] neg_hi:[0,1,0]
	ds_read_b128 v[144:147], v2 offset:17152
	ds_read_b64 v[164:165], v3 offset:13056
	ds_read_b128 v[156:159], v2 offset:8960
	ds_read_b128 v[148:151], v2 offset:4864
	ds_read_b128 v[152:155], v2 offset:21248
	s_waitcnt lgkmcnt(6)
	v_pk_mul_f32 v[46:47], v[16:17], v[24:25] op_sel_hi:[1,0]
	v_pk_mul_f32 v[50:51], v[16:17], v[160:161] op_sel_hi:[1,0]
	v_pk_fma_f32 v[46:47], v[18:19], v[24:25], v[46:47] op_sel:[0,1,0] op_sel_hi:[1,1,1]
	v_pk_fma_f32 v[50:51], v[18:19], v[160:161], v[50:51] op_sel:[0,1,0] op_sel_hi:[1,1,1]
	v_pk_fma_f32 v[46:47], v[20:21], v[26:27], v[46:47] op_sel_hi:[1,0,1]
	v_pk_fma_f32 v[50:51], v[20:21], v[162:163], v[50:51] op_sel_hi:[1,0,1]
	v_pk_fma_f32 v[46:47], v[22:23], v[26:27], v[46:47] op_sel:[0,1,0] op_sel_hi:[1,1,1]
	v_pk_fma_f32 v[50:51], v[22:23], v[162:163], v[50:51] op_sel:[0,1,0] op_sel_hi:[1,1,1]
	ds_read_b128 v[160:163], v2 offset:768
	v_pk_mul_f32 v[168:169], v[44:45], v[36:37] op_sel_hi:[1,0]
	v_add_f32_dpp v48, v47, v46 quad_perm:[1,0,3,2] row_mask:0xf bank_mask:0xf bound_ctrl:1
	v_add_f32_dpp v52, v51, v50 quad_perm:[1,0,3,2] row_mask:0xf bank_mask:0xf bound_ctrl:1
	v_pk_mul_f32 v[170:171], v[44:45], v[36:37] op_sel:[0,1] op_sel_hi:[1,1]
	v_add_f32_dpp v48, v48, v48 quad_perm:[2,3,0,1] row_mask:0xf bank_mask:0xf bound_ctrl:1
	ds_write_b32 v0, v52 offset:50176
	v_pk_mul_f32 v[172:173], v[44:45], v[38:39] op_sel_hi:[1,0]
	v_pk_mul_f32 v[174:175], v[44:45], v[38:39] op_sel:[0,1] op_sel_hi:[1,1]
	v_add_f32_dpp v48, v48, v48 row_ror:4 row_mask:0xf bank_mask:0xf bound_ctrl:1
	v_pk_fma_f32 v[168:169], v[16:17], v[28:29], v[168:169] op_sel_hi:[1,0,1]
	v_pk_fma_f32 v[170:171], v[18:19], v[28:29], v[170:171] op_sel:[0,1,0] op_sel_hi:[1,1,1]
	v_add_f32_dpp v48, v48, v48 row_ror:8 row_mask:0xf bank_mask:0xf bound_ctrl:1
	v_pk_fma_f32 v[172:173], v[20:21], v[30:31], v[172:173] op_sel_hi:[1,0,1]
	v_pk_fma_f32 v[174:175], v[22:23], v[30:31], v[174:175] op_sel:[0,1,0] op_sel_hi:[1,1,1]
	v_mov_b32_dpp v49, v48 quad_perm:[1,0,3,2] row_mask:0xf bank_mask:0xf bound_ctrl:1
	v_pk_fma_f32 v[16:17], v[48:49], v[32:33], v[168:169] op_sel_hi:[1,0,1] neg_lo:[0,1,0] neg_hi:[0,1,0]
	v_pk_fma_f32 v[18:19], v[48:49], v[32:33], v[170:171] op_sel:[0,1,0] op_sel_hi:[1,1,1] neg_lo:[0,1,0] neg_hi:[0,1,0]
	v_pk_fma_f32 v[20:21], v[48:49], v[34:35], v[172:173] op_sel_hi:[1,0,1] neg_lo:[0,1,0] neg_hi:[0,1,0]
	v_pk_fma_f32 v[22:23], v[48:49], v[34:35], v[174:175] op_sel:[0,1,0] op_sel_hi:[1,1,1] neg_lo:[0,1,0] neg_hi:[0,1,0]
	ds_read_b128 v[24:27], v2 offset:17408
	ds_read_b64 v[44:45], v3 offset:13312
	ds_read_b128 v[36:39], v2 offset:9216
	ds_read_b128 v[28:31], v2 offset:5120
	ds_read_b128 v[32:35], v2 offset:21504
	s_waitcnt lgkmcnt(6)
	v_pk_mul_f32 v[46:47], v[16:17], v[144:145] op_sel_hi:[1,0]
	v_pk_mul_f32 v[50:51], v[16:17], v[40:41] op_sel_hi:[1,0]
	v_pk_fma_f32 v[46:47], v[18:19], v[144:145], v[46:47] op_sel:[0,1,0] op_sel_hi:[1,1,1]
	v_pk_fma_f32 v[50:51], v[18:19], v[40:41], v[50:51] op_sel:[0,1,0] op_sel_hi:[1,1,1]
	v_pk_fma_f32 v[46:47], v[20:21], v[146:147], v[46:47] op_sel_hi:[1,0,1]
	v_pk_fma_f32 v[50:51], v[20:21], v[42:43], v[50:51] op_sel_hi:[1,0,1]
	v_pk_fma_f32 v[46:47], v[22:23], v[146:147], v[46:47] op_sel:[0,1,0] op_sel_hi:[1,1,1]
	v_pk_fma_f32 v[50:51], v[22:23], v[42:43], v[50:51] op_sel:[0,1,0] op_sel_hi:[1,1,1]
	ds_read_b128 v[40:43], v2 offset:1024
	v_pk_mul_f32 v[168:169], v[164:165], v[156:157] op_sel_hi:[1,0]
	v_add_f32_dpp v48, v47, v46 quad_perm:[1,0,3,2] row_mask:0xf bank_mask:0xf bound_ctrl:1
	v_add_f32_dpp v52, v51, v50 quad_perm:[1,0,3,2] row_mask:0xf bank_mask:0xf bound_ctrl:1
	v_pk_mul_f32 v[170:171], v[164:165], v[156:157] op_sel:[0,1] op_sel_hi:[1,1]
	v_add_f32_dpp v48, v48, v48 quad_perm:[2,3,0,1] row_mask:0xf bank_mask:0xf bound_ctrl:1
	ds_write_b32 v0, v52 offset:51200
	v_pk_mul_f32 v[172:173], v[164:165], v[158:159] op_sel_hi:[1,0]
	v_pk_mul_f32 v[174:175], v[164:165], v[158:159] op_sel:[0,1] op_sel_hi:[1,1]
	v_add_f32_dpp v48, v48, v48 row_ror:4 row_mask:0xf bank_mask:0xf bound_ctrl:1
	v_pk_fma_f32 v[168:169], v[16:17], v[148:149], v[168:169] op_sel_hi:[1,0,1]
	v_pk_fma_f32 v[170:171], v[18:19], v[148:149], v[170:171] op_sel:[0,1,0] op_sel_hi:[1,1,1]
	v_add_f32_dpp v48, v48, v48 row_ror:8 row_mask:0xf bank_mask:0xf bound_ctrl:1
	v_pk_fma_f32 v[172:173], v[20:21], v[150:151], v[172:173] op_sel_hi:[1,0,1]
	v_pk_fma_f32 v[174:175], v[22:23], v[150:151], v[174:175] op_sel:[0,1,0] op_sel_hi:[1,1,1]
	v_mov_b32_dpp v49, v48 quad_perm:[1,0,3,2] row_mask:0xf bank_mask:0xf bound_ctrl:1
	v_pk_fma_f32 v[16:17], v[48:49], v[152:153], v[168:169] op_sel_hi:[1,0,1] neg_lo:[0,1,0] neg_hi:[0,1,0]
	v_pk_fma_f32 v[18:19], v[48:49], v[152:153], v[170:171] op_sel:[0,1,0] op_sel_hi:[1,1,1] neg_lo:[0,1,0] neg_hi:[0,1,0]
	v_pk_fma_f32 v[20:21], v[48:49], v[154:155], v[172:173] op_sel_hi:[1,0,1] neg_lo:[0,1,0] neg_hi:[0,1,0]
	v_pk_fma_f32 v[22:23], v[48:49], v[154:155], v[174:175] op_sel:[0,1,0] op_sel_hi:[1,1,1] neg_lo:[0,1,0] neg_hi:[0,1,0]
	ds_read_b128 v[144:147], v2 offset:17664
	ds_read_b64 v[164:165], v3 offset:13568
	ds_read_b128 v[156:159], v2 offset:9472
	ds_read_b128 v[148:151], v2 offset:5376
	ds_read_b128 v[152:155], v2 offset:21760
	s_waitcnt lgkmcnt(6)
	v_pk_mul_f32 v[46:47], v[16:17], v[24:25] op_sel_hi:[1,0]
	v_pk_mul_f32 v[50:51], v[16:17], v[160:161] op_sel_hi:[1,0]
	v_pk_fma_f32 v[46:47], v[18:19], v[24:25], v[46:47] op_sel:[0,1,0] op_sel_hi:[1,1,1]
	v_pk_fma_f32 v[50:51], v[18:19], v[160:161], v[50:51] op_sel:[0,1,0] op_sel_hi:[1,1,1]
	v_pk_fma_f32 v[46:47], v[20:21], v[26:27], v[46:47] op_sel_hi:[1,0,1]
	v_pk_fma_f32 v[50:51], v[20:21], v[162:163], v[50:51] op_sel_hi:[1,0,1]
	v_pk_fma_f32 v[46:47], v[22:23], v[26:27], v[46:47] op_sel:[0,1,0] op_sel_hi:[1,1,1]
	v_pk_fma_f32 v[50:51], v[22:23], v[162:163], v[50:51] op_sel:[0,1,0] op_sel_hi:[1,1,1]
	ds_read_b128 v[160:163], v2 offset:1280
	v_pk_mul_f32 v[168:169], v[44:45], v[36:37] op_sel_hi:[1,0]
	v_add_f32_dpp v48, v47, v46 quad_perm:[1,0,3,2] row_mask:0xf bank_mask:0xf bound_ctrl:1
	v_add_f32_dpp v52, v51, v50 quad_perm:[1,0,3,2] row_mask:0xf bank_mask:0xf bound_ctrl:1
	v_pk_mul_f32 v[170:171], v[44:45], v[36:37] op_sel:[0,1] op_sel_hi:[1,1]
	v_add_f32_dpp v48, v48, v48 quad_perm:[2,3,0,1] row_mask:0xf bank_mask:0xf bound_ctrl:1
	ds_write_b32 v0, v52 offset:52224
	v_pk_mul_f32 v[172:173], v[44:45], v[38:39] op_sel_hi:[1,0]
	v_pk_mul_f32 v[174:175], v[44:45], v[38:39] op_sel:[0,1] op_sel_hi:[1,1]
	v_add_f32_dpp v48, v48, v48 row_ror:4 row_mask:0xf bank_mask:0xf bound_ctrl:1
	v_pk_fma_f32 v[168:169], v[16:17], v[28:29], v[168:169] op_sel_hi:[1,0,1]
	v_pk_fma_f32 v[170:171], v[18:19], v[28:29], v[170:171] op_sel:[0,1,0] op_sel_hi:[1,1,1]
	v_add_f32_dpp v48, v48, v48 row_ror:8 row_mask:0xf bank_mask:0xf bound_ctrl:1
	v_pk_fma_f32 v[172:173], v[20:21], v[30:31], v[172:173] op_sel_hi:[1,0,1]
	v_pk_fma_f32 v[174:175], v[22:23], v[30:31], v[174:175] op_sel:[0,1,0] op_sel_hi:[1,1,1]
	v_mov_b32_dpp v49, v48 quad_perm:[1,0,3,2] row_mask:0xf bank_mask:0xf bound_ctrl:1
	v_pk_fma_f32 v[16:17], v[48:49], v[32:33], v[168:169] op_sel_hi:[1,0,1] neg_lo:[0,1,0] neg_hi:[0,1,0]
	v_pk_fma_f32 v[18:19], v[48:49], v[32:33], v[170:171] op_sel:[0,1,0] op_sel_hi:[1,1,1] neg_lo:[0,1,0] neg_hi:[0,1,0]
	v_pk_fma_f32 v[20:21], v[48:49], v[34:35], v[172:173] op_sel_hi:[1,0,1] neg_lo:[0,1,0] neg_hi:[0,1,0]
	v_pk_fma_f32 v[22:23], v[48:49], v[34:35], v[174:175] op_sel:[0,1,0] op_sel_hi:[1,1,1] neg_lo:[0,1,0] neg_hi:[0,1,0]
	ds_read_b128 v[24:27], v2 offset:17920
	ds_read_b64 v[44:45], v3 offset:13824
	ds_read_b128 v[36:39], v2 offset:9728
	ds_read_b128 v[28:31], v2 offset:5632
	ds_read_b128 v[32:35], v2 offset:22016
	s_waitcnt lgkmcnt(6)
	v_pk_mul_f32 v[46:47], v[16:17], v[144:145] op_sel_hi:[1,0]
	v_pk_mul_f32 v[50:51], v[16:17], v[40:41] op_sel_hi:[1,0]
	v_pk_fma_f32 v[46:47], v[18:19], v[144:145], v[46:47] op_sel:[0,1,0] op_sel_hi:[1,1,1]
	v_pk_fma_f32 v[50:51], v[18:19], v[40:41], v[50:51] op_sel:[0,1,0] op_sel_hi:[1,1,1]
	v_pk_fma_f32 v[46:47], v[20:21], v[146:147], v[46:47] op_sel_hi:[1,0,1]
	v_pk_fma_f32 v[50:51], v[20:21], v[42:43], v[50:51] op_sel_hi:[1,0,1]
	v_pk_fma_f32 v[46:47], v[22:23], v[146:147], v[46:47] op_sel:[0,1,0] op_sel_hi:[1,1,1]
	v_pk_fma_f32 v[50:51], v[22:23], v[42:43], v[50:51] op_sel:[0,1,0] op_sel_hi:[1,1,1]
	ds_read_b128 v[40:43], v2 offset:1536
	v_pk_mul_f32 v[168:169], v[164:165], v[156:157] op_sel_hi:[1,0]
	v_add_f32_dpp v48, v47, v46 quad_perm:[1,0,3,2] row_mask:0xf bank_mask:0xf bound_ctrl:1
	v_add_f32_dpp v52, v51, v50 quad_perm:[1,0,3,2] row_mask:0xf bank_mask:0xf bound_ctrl:1
	v_pk_mul_f32 v[170:171], v[164:165], v[156:157] op_sel:[0,1] op_sel_hi:[1,1]
	v_add_f32_dpp v48, v48, v48 quad_perm:[2,3,0,1] row_mask:0xf bank_mask:0xf bound_ctrl:1
	ds_write_b32 v0, v52 offset:53248
	v_pk_mul_f32 v[172:173], v[164:165], v[158:159] op_sel_hi:[1,0]
	v_pk_mul_f32 v[174:175], v[164:165], v[158:159] op_sel:[0,1] op_sel_hi:[1,1]
	v_add_f32_dpp v48, v48, v48 row_ror:4 row_mask:0xf bank_mask:0xf bound_ctrl:1
	v_pk_fma_f32 v[168:169], v[16:17], v[148:149], v[168:169] op_sel_hi:[1,0,1]
	v_pk_fma_f32 v[170:171], v[18:19], v[148:149], v[170:171] op_sel:[0,1,0] op_sel_hi:[1,1,1]
	v_add_f32_dpp v48, v48, v48 row_ror:8 row_mask:0xf bank_mask:0xf bound_ctrl:1
	v_pk_fma_f32 v[172:173], v[20:21], v[150:151], v[172:173] op_sel_hi:[1,0,1]
	v_pk_fma_f32 v[174:175], v[22:23], v[150:151], v[174:175] op_sel:[0,1,0] op_sel_hi:[1,1,1]
	v_mov_b32_dpp v49, v48 quad_perm:[1,0,3,2] row_mask:0xf bank_mask:0xf bound_ctrl:1
	v_pk_fma_f32 v[16:17], v[48:49], v[152:153], v[168:169] op_sel_hi:[1,0,1] neg_lo:[0,1,0] neg_hi:[0,1,0]
	v_pk_fma_f32 v[18:19], v[48:49], v[152:153], v[170:171] op_sel:[0,1,0] op_sel_hi:[1,1,1] neg_lo:[0,1,0] neg_hi:[0,1,0]
	v_pk_fma_f32 v[20:21], v[48:49], v[154:155], v[172:173] op_sel_hi:[1,0,1] neg_lo:[0,1,0] neg_hi:[0,1,0]
	v_pk_fma_f32 v[22:23], v[48:49], v[154:155], v[174:175] op_sel:[0,1,0] op_sel_hi:[1,1,1] neg_lo:[0,1,0] neg_hi:[0,1,0]
	ds_read_b128 v[144:147], v2 offset:18176
	ds_read_b64 v[164:165], v3 offset:14080
	ds_read_b128 v[156:159], v2 offset:9984
	ds_read_b128 v[148:151], v2 offset:5888
	ds_read_b128 v[152:155], v2 offset:22272
	s_waitcnt lgkmcnt(6)
	v_pk_mul_f32 v[46:47], v[16:17], v[24:25] op_sel_hi:[1,0]
	v_pk_mul_f32 v[50:51], v[16:17], v[160:161] op_sel_hi:[1,0]
	v_pk_fma_f32 v[46:47], v[18:19], v[24:25], v[46:47] op_sel:[0,1,0] op_sel_hi:[1,1,1]
	v_pk_fma_f32 v[50:51], v[18:19], v[160:161], v[50:51] op_sel:[0,1,0] op_sel_hi:[1,1,1]
	v_pk_fma_f32 v[46:47], v[20:21], v[26:27], v[46:47] op_sel_hi:[1,0,1]
	v_pk_fma_f32 v[50:51], v[20:21], v[162:163], v[50:51] op_sel_hi:[1,0,1]
	v_pk_fma_f32 v[46:47], v[22:23], v[26:27], v[46:47] op_sel:[0,1,0] op_sel_hi:[1,1,1]
	v_pk_fma_f32 v[50:51], v[22:23], v[162:163], v[50:51] op_sel:[0,1,0] op_sel_hi:[1,1,1]
	ds_read_b128 v[160:163], v2 offset:1792
	v_pk_mul_f32 v[168:169], v[44:45], v[36:37] op_sel_hi:[1,0]
	v_add_f32_dpp v48, v47, v46 quad_perm:[1,0,3,2] row_mask:0xf bank_mask:0xf bound_ctrl:1
	v_add_f32_dpp v52, v51, v50 quad_perm:[1,0,3,2] row_mask:0xf bank_mask:0xf bound_ctrl:1
	v_pk_mul_f32 v[170:171], v[44:45], v[36:37] op_sel:[0,1] op_sel_hi:[1,1]
	v_add_f32_dpp v48, v48, v48 quad_perm:[2,3,0,1] row_mask:0xf bank_mask:0xf bound_ctrl:1
	ds_write_b32 v0, v52 offset:54272
	v_pk_mul_f32 v[172:173], v[44:45], v[38:39] op_sel_hi:[1,0]
	v_pk_mul_f32 v[174:175], v[44:45], v[38:39] op_sel:[0,1] op_sel_hi:[1,1]
	v_add_f32_dpp v48, v48, v48 row_ror:4 row_mask:0xf bank_mask:0xf bound_ctrl:1
	v_pk_fma_f32 v[168:169], v[16:17], v[28:29], v[168:169] op_sel_hi:[1,0,1]
	v_pk_fma_f32 v[170:171], v[18:19], v[28:29], v[170:171] op_sel:[0,1,0] op_sel_hi:[1,1,1]
	v_add_f32_dpp v48, v48, v48 row_ror:8 row_mask:0xf bank_mask:0xf bound_ctrl:1
	v_pk_fma_f32 v[172:173], v[20:21], v[30:31], v[172:173] op_sel_hi:[1,0,1]
	v_pk_fma_f32 v[174:175], v[22:23], v[30:31], v[174:175] op_sel:[0,1,0] op_sel_hi:[1,1,1]
	v_mov_b32_dpp v49, v48 quad_perm:[1,0,3,2] row_mask:0xf bank_mask:0xf bound_ctrl:1
	v_pk_fma_f32 v[16:17], v[48:49], v[32:33], v[168:169] op_sel_hi:[1,0,1] neg_lo:[0,1,0] neg_hi:[0,1,0]
	v_pk_fma_f32 v[18:19], v[48:49], v[32:33], v[170:171] op_sel:[0,1,0] op_sel_hi:[1,1,1] neg_lo:[0,1,0] neg_hi:[0,1,0]
	v_pk_fma_f32 v[20:21], v[48:49], v[34:35], v[172:173] op_sel_hi:[1,0,1] neg_lo:[0,1,0] neg_hi:[0,1,0]
	v_pk_fma_f32 v[22:23], v[48:49], v[34:35], v[174:175] op_sel:[0,1,0] op_sel_hi:[1,1,1] neg_lo:[0,1,0] neg_hi:[0,1,0]
	ds_read_b128 v[24:27], v2 offset:18432
	ds_read_b64 v[44:45], v3 offset:14336
	ds_read_b128 v[36:39], v2 offset:10240
	ds_read_b128 v[28:31], v2 offset:6144
	ds_read_b128 v[32:35], v2 offset:22528
	s_waitcnt lgkmcnt(6)
	v_pk_mul_f32 v[46:47], v[16:17], v[144:145] op_sel_hi:[1,0]
	v_pk_mul_f32 v[50:51], v[16:17], v[40:41] op_sel_hi:[1,0]
	v_pk_fma_f32 v[46:47], v[18:19], v[144:145], v[46:47] op_sel:[0,1,0] op_sel_hi:[1,1,1]
	v_pk_fma_f32 v[50:51], v[18:19], v[40:41], v[50:51] op_sel:[0,1,0] op_sel_hi:[1,1,1]
	v_pk_fma_f32 v[46:47], v[20:21], v[146:147], v[46:47] op_sel_hi:[1,0,1]
	v_pk_fma_f32 v[50:51], v[20:21], v[42:43], v[50:51] op_sel_hi:[1,0,1]
	v_pk_fma_f32 v[46:47], v[22:23], v[146:147], v[46:47] op_sel:[0,1,0] op_sel_hi:[1,1,1]
	v_pk_fma_f32 v[50:51], v[22:23], v[42:43], v[50:51] op_sel:[0,1,0] op_sel_hi:[1,1,1]
	ds_read_b128 v[40:43], v2 offset:2048
	v_pk_mul_f32 v[168:169], v[164:165], v[156:157] op_sel_hi:[1,0]
	v_add_f32_dpp v48, v47, v46 quad_perm:[1,0,3,2] row_mask:0xf bank_mask:0xf bound_ctrl:1
	v_add_f32_dpp v52, v51, v50 quad_perm:[1,0,3,2] row_mask:0xf bank_mask:0xf bound_ctrl:1
	v_pk_mul_f32 v[170:171], v[164:165], v[156:157] op_sel:[0,1] op_sel_hi:[1,1]
	v_add_f32_dpp v48, v48, v48 quad_perm:[2,3,0,1] row_mask:0xf bank_mask:0xf bound_ctrl:1
	ds_write_b32 v0, v52 offset:55296
	v_pk_mul_f32 v[172:173], v[164:165], v[158:159] op_sel_hi:[1,0]
	v_pk_mul_f32 v[174:175], v[164:165], v[158:159] op_sel:[0,1] op_sel_hi:[1,1]
	v_add_f32_dpp v48, v48, v48 row_ror:4 row_mask:0xf bank_mask:0xf bound_ctrl:1
	v_pk_fma_f32 v[168:169], v[16:17], v[148:149], v[168:169] op_sel_hi:[1,0,1]
	v_pk_fma_f32 v[170:171], v[18:19], v[148:149], v[170:171] op_sel:[0,1,0] op_sel_hi:[1,1,1]
	v_add_f32_dpp v48, v48, v48 row_ror:8 row_mask:0xf bank_mask:0xf bound_ctrl:1
	v_pk_fma_f32 v[172:173], v[20:21], v[150:151], v[172:173] op_sel_hi:[1,0,1]
	v_pk_fma_f32 v[174:175], v[22:23], v[150:151], v[174:175] op_sel:[0,1,0] op_sel_hi:[1,1,1]
	v_mov_b32_dpp v49, v48 quad_perm:[1,0,3,2] row_mask:0xf bank_mask:0xf bound_ctrl:1
	v_pk_fma_f32 v[16:17], v[48:49], v[152:153], v[168:169] op_sel_hi:[1,0,1] neg_lo:[0,1,0] neg_hi:[0,1,0]
	v_pk_fma_f32 v[18:19], v[48:49], v[152:153], v[170:171] op_sel:[0,1,0] op_sel_hi:[1,1,1] neg_lo:[0,1,0] neg_hi:[0,1,0]
	v_pk_fma_f32 v[20:21], v[48:49], v[154:155], v[172:173] op_sel_hi:[1,0,1] neg_lo:[0,1,0] neg_hi:[0,1,0]
	v_pk_fma_f32 v[22:23], v[48:49], v[154:155], v[174:175] op_sel:[0,1,0] op_sel_hi:[1,1,1] neg_lo:[0,1,0] neg_hi:[0,1,0]
	ds_read_b128 v[144:147], v2 offset:18688
	ds_read_b64 v[164:165], v3 offset:14592
	ds_read_b128 v[156:159], v2 offset:10496
	ds_read_b128 v[148:151], v2 offset:6400
	ds_read_b128 v[152:155], v2 offset:22784
	s_waitcnt lgkmcnt(6)
	v_pk_mul_f32 v[46:47], v[16:17], v[24:25] op_sel_hi:[1,0]
	v_pk_mul_f32 v[50:51], v[16:17], v[160:161] op_sel_hi:[1,0]
	v_pk_fma_f32 v[46:47], v[18:19], v[24:25], v[46:47] op_sel:[0,1,0] op_sel_hi:[1,1,1]
	v_pk_fma_f32 v[50:51], v[18:19], v[160:161], v[50:51] op_sel:[0,1,0] op_sel_hi:[1,1,1]
	v_pk_fma_f32 v[46:47], v[20:21], v[26:27], v[46:47] op_sel_hi:[1,0,1]
	v_pk_fma_f32 v[50:51], v[20:21], v[162:163], v[50:51] op_sel_hi:[1,0,1]
	v_pk_fma_f32 v[46:47], v[22:23], v[26:27], v[46:47] op_sel:[0,1,0] op_sel_hi:[1,1,1]
	v_pk_fma_f32 v[50:51], v[22:23], v[162:163], v[50:51] op_sel:[0,1,0] op_sel_hi:[1,1,1]
	ds_read_b128 v[160:163], v2 offset:2304
	v_pk_mul_f32 v[168:169], v[44:45], v[36:37] op_sel_hi:[1,0]
	v_add_f32_dpp v48, v47, v46 quad_perm:[1,0,3,2] row_mask:0xf bank_mask:0xf bound_ctrl:1
	v_add_f32_dpp v52, v51, v50 quad_perm:[1,0,3,2] row_mask:0xf bank_mask:0xf bound_ctrl:1
	v_pk_mul_f32 v[170:171], v[44:45], v[36:37] op_sel:[0,1] op_sel_hi:[1,1]
	v_add_f32_dpp v48, v48, v48 quad_perm:[2,3,0,1] row_mask:0xf bank_mask:0xf bound_ctrl:1
	ds_write_b32 v0, v52 offset:56320
	v_pk_mul_f32 v[172:173], v[44:45], v[38:39] op_sel_hi:[1,0]
	v_pk_mul_f32 v[174:175], v[44:45], v[38:39] op_sel:[0,1] op_sel_hi:[1,1]
	v_add_f32_dpp v48, v48, v48 row_ror:4 row_mask:0xf bank_mask:0xf bound_ctrl:1
	v_pk_fma_f32 v[168:169], v[16:17], v[28:29], v[168:169] op_sel_hi:[1,0,1]
	v_pk_fma_f32 v[170:171], v[18:19], v[28:29], v[170:171] op_sel:[0,1,0] op_sel_hi:[1,1,1]
	v_add_f32_dpp v48, v48, v48 row_ror:8 row_mask:0xf bank_mask:0xf bound_ctrl:1
	v_pk_fma_f32 v[172:173], v[20:21], v[30:31], v[172:173] op_sel_hi:[1,0,1]
	v_pk_fma_f32 v[174:175], v[22:23], v[30:31], v[174:175] op_sel:[0,1,0] op_sel_hi:[1,1,1]
	v_mov_b32_dpp v49, v48 quad_perm:[1,0,3,2] row_mask:0xf bank_mask:0xf bound_ctrl:1
	v_pk_fma_f32 v[16:17], v[48:49], v[32:33], v[168:169] op_sel_hi:[1,0,1] neg_lo:[0,1,0] neg_hi:[0,1,0]
	v_pk_fma_f32 v[18:19], v[48:49], v[32:33], v[170:171] op_sel:[0,1,0] op_sel_hi:[1,1,1] neg_lo:[0,1,0] neg_hi:[0,1,0]
	v_pk_fma_f32 v[20:21], v[48:49], v[34:35], v[172:173] op_sel_hi:[1,0,1] neg_lo:[0,1,0] neg_hi:[0,1,0]
	v_pk_fma_f32 v[22:23], v[48:49], v[34:35], v[174:175] op_sel:[0,1,0] op_sel_hi:[1,1,1] neg_lo:[0,1,0] neg_hi:[0,1,0]
	ds_read_b128 v[24:27], v2 offset:18944
	ds_read_b64 v[44:45], v3 offset:14848
	ds_read_b128 v[36:39], v2 offset:10752
	ds_read_b128 v[28:31], v2 offset:6656
	ds_read_b128 v[32:35], v2 offset:23040
	s_waitcnt lgkmcnt(6)
	v_pk_mul_f32 v[46:47], v[16:17], v[144:145] op_sel_hi:[1,0]
	v_pk_mul_f32 v[50:51], v[16:17], v[40:41] op_sel_hi:[1,0]
	v_pk_fma_f32 v[46:47], v[18:19], v[144:145], v[46:47] op_sel:[0,1,0] op_sel_hi:[1,1,1]
	v_pk_fma_f32 v[50:51], v[18:19], v[40:41], v[50:51] op_sel:[0,1,0] op_sel_hi:[1,1,1]
	v_pk_fma_f32 v[46:47], v[20:21], v[146:147], v[46:47] op_sel_hi:[1,0,1]
	v_pk_fma_f32 v[50:51], v[20:21], v[42:43], v[50:51] op_sel_hi:[1,0,1]
	v_pk_fma_f32 v[46:47], v[22:23], v[146:147], v[46:47] op_sel:[0,1,0] op_sel_hi:[1,1,1]
	v_pk_fma_f32 v[50:51], v[22:23], v[42:43], v[50:51] op_sel:[0,1,0] op_sel_hi:[1,1,1]
	ds_read_b128 v[40:43], v2 offset:2560
	v_pk_mul_f32 v[168:169], v[164:165], v[156:157] op_sel_hi:[1,0]
	v_add_f32_dpp v48, v47, v46 quad_perm:[1,0,3,2] row_mask:0xf bank_mask:0xf bound_ctrl:1
	v_add_f32_dpp v52, v51, v50 quad_perm:[1,0,3,2] row_mask:0xf bank_mask:0xf bound_ctrl:1
	v_pk_mul_f32 v[170:171], v[164:165], v[156:157] op_sel:[0,1] op_sel_hi:[1,1]
	v_add_f32_dpp v48, v48, v48 quad_perm:[2,3,0,1] row_mask:0xf bank_mask:0xf bound_ctrl:1
	ds_write_b32 v0, v52 offset:57344
	v_pk_mul_f32 v[172:173], v[164:165], v[158:159] op_sel_hi:[1,0]
	v_pk_mul_f32 v[174:175], v[164:165], v[158:159] op_sel:[0,1] op_sel_hi:[1,1]
	v_add_f32_dpp v48, v48, v48 row_ror:4 row_mask:0xf bank_mask:0xf bound_ctrl:1
	v_pk_fma_f32 v[168:169], v[16:17], v[148:149], v[168:169] op_sel_hi:[1,0,1]
	v_pk_fma_f32 v[170:171], v[18:19], v[148:149], v[170:171] op_sel:[0,1,0] op_sel_hi:[1,1,1]
	v_add_f32_dpp v48, v48, v48 row_ror:8 row_mask:0xf bank_mask:0xf bound_ctrl:1
	v_pk_fma_f32 v[172:173], v[20:21], v[150:151], v[172:173] op_sel_hi:[1,0,1]
	v_pk_fma_f32 v[174:175], v[22:23], v[150:151], v[174:175] op_sel:[0,1,0] op_sel_hi:[1,1,1]
	v_mov_b32_dpp v49, v48 quad_perm:[1,0,3,2] row_mask:0xf bank_mask:0xf bound_ctrl:1
	v_pk_fma_f32 v[16:17], v[48:49], v[152:153], v[168:169] op_sel_hi:[1,0,1] neg_lo:[0,1,0] neg_hi:[0,1,0]
	v_pk_fma_f32 v[18:19], v[48:49], v[152:153], v[170:171] op_sel:[0,1,0] op_sel_hi:[1,1,1] neg_lo:[0,1,0] neg_hi:[0,1,0]
	v_pk_fma_f32 v[20:21], v[48:49], v[154:155], v[172:173] op_sel_hi:[1,0,1] neg_lo:[0,1,0] neg_hi:[0,1,0]
	v_pk_fma_f32 v[22:23], v[48:49], v[154:155], v[174:175] op_sel:[0,1,0] op_sel_hi:[1,1,1] neg_lo:[0,1,0] neg_hi:[0,1,0]
	ds_read_b128 v[144:147], v2 offset:19200
	ds_read_b64 v[164:165], v3 offset:15104
	ds_read_b128 v[156:159], v2 offset:11008
	ds_read_b128 v[148:151], v2 offset:6912
	ds_read_b128 v[152:155], v2 offset:23296
	s_waitcnt lgkmcnt(6)
	v_pk_mul_f32 v[46:47], v[16:17], v[24:25] op_sel_hi:[1,0]
	v_pk_mul_f32 v[50:51], v[16:17], v[160:161] op_sel_hi:[1,0]
	v_pk_fma_f32 v[46:47], v[18:19], v[24:25], v[46:47] op_sel:[0,1,0] op_sel_hi:[1,1,1]
	v_pk_fma_f32 v[50:51], v[18:19], v[160:161], v[50:51] op_sel:[0,1,0] op_sel_hi:[1,1,1]
	v_pk_fma_f32 v[46:47], v[20:21], v[26:27], v[46:47] op_sel_hi:[1,0,1]
	v_pk_fma_f32 v[50:51], v[20:21], v[162:163], v[50:51] op_sel_hi:[1,0,1]
	v_pk_fma_f32 v[46:47], v[22:23], v[26:27], v[46:47] op_sel:[0,1,0] op_sel_hi:[1,1,1]
	v_pk_fma_f32 v[50:51], v[22:23], v[162:163], v[50:51] op_sel:[0,1,0] op_sel_hi:[1,1,1]
	ds_read_b128 v[160:163], v2 offset:2816
	v_pk_mul_f32 v[168:169], v[44:45], v[36:37] op_sel_hi:[1,0]
	v_add_f32_dpp v48, v47, v46 quad_perm:[1,0,3,2] row_mask:0xf bank_mask:0xf bound_ctrl:1
	v_add_f32_dpp v52, v51, v50 quad_perm:[1,0,3,2] row_mask:0xf bank_mask:0xf bound_ctrl:1
	v_pk_mul_f32 v[170:171], v[44:45], v[36:37] op_sel:[0,1] op_sel_hi:[1,1]
	v_add_f32_dpp v48, v48, v48 quad_perm:[2,3,0,1] row_mask:0xf bank_mask:0xf bound_ctrl:1
	ds_write_b32 v0, v52 offset:58368
	v_pk_mul_f32 v[172:173], v[44:45], v[38:39] op_sel_hi:[1,0]
	v_pk_mul_f32 v[174:175], v[44:45], v[38:39] op_sel:[0,1] op_sel_hi:[1,1]
	v_add_f32_dpp v48, v48, v48 row_ror:4 row_mask:0xf bank_mask:0xf bound_ctrl:1
	v_pk_fma_f32 v[168:169], v[16:17], v[28:29], v[168:169] op_sel_hi:[1,0,1]
	v_pk_fma_f32 v[170:171], v[18:19], v[28:29], v[170:171] op_sel:[0,1,0] op_sel_hi:[1,1,1]
	v_add_f32_dpp v48, v48, v48 row_ror:8 row_mask:0xf bank_mask:0xf bound_ctrl:1
	v_pk_fma_f32 v[172:173], v[20:21], v[30:31], v[172:173] op_sel_hi:[1,0,1]
	v_pk_fma_f32 v[174:175], v[22:23], v[30:31], v[174:175] op_sel:[0,1,0] op_sel_hi:[1,1,1]
	v_mov_b32_dpp v49, v48 quad_perm:[1,0,3,2] row_mask:0xf bank_mask:0xf bound_ctrl:1
	v_pk_fma_f32 v[16:17], v[48:49], v[32:33], v[168:169] op_sel_hi:[1,0,1] neg_lo:[0,1,0] neg_hi:[0,1,0]
	v_pk_fma_f32 v[18:19], v[48:49], v[32:33], v[170:171] op_sel:[0,1,0] op_sel_hi:[1,1,1] neg_lo:[0,1,0] neg_hi:[0,1,0]
	v_pk_fma_f32 v[20:21], v[48:49], v[34:35], v[172:173] op_sel_hi:[1,0,1] neg_lo:[0,1,0] neg_hi:[0,1,0]
	v_pk_fma_f32 v[22:23], v[48:49], v[34:35], v[174:175] op_sel:[0,1,0] op_sel_hi:[1,1,1] neg_lo:[0,1,0] neg_hi:[0,1,0]
	ds_read_b128 v[24:27], v2 offset:19456
	ds_read_b64 v[44:45], v3 offset:15360
	ds_read_b128 v[36:39], v2 offset:11264
	ds_read_b128 v[28:31], v2 offset:7168
	ds_read_b128 v[32:35], v2 offset:23552
	s_waitcnt lgkmcnt(6)
	v_pk_mul_f32 v[46:47], v[16:17], v[144:145] op_sel_hi:[1,0]
	v_pk_mul_f32 v[50:51], v[16:17], v[40:41] op_sel_hi:[1,0]
	v_pk_fma_f32 v[46:47], v[18:19], v[144:145], v[46:47] op_sel:[0,1,0] op_sel_hi:[1,1,1]
	v_pk_fma_f32 v[50:51], v[18:19], v[40:41], v[50:51] op_sel:[0,1,0] op_sel_hi:[1,1,1]
	v_pk_fma_f32 v[46:47], v[20:21], v[146:147], v[46:47] op_sel_hi:[1,0,1]
	v_pk_fma_f32 v[50:51], v[20:21], v[42:43], v[50:51] op_sel_hi:[1,0,1]
	v_pk_fma_f32 v[46:47], v[22:23], v[146:147], v[46:47] op_sel:[0,1,0] op_sel_hi:[1,1,1]
	v_pk_fma_f32 v[50:51], v[22:23], v[42:43], v[50:51] op_sel:[0,1,0] op_sel_hi:[1,1,1]
	ds_read_b128 v[40:43], v2 offset:3072
	v_pk_mul_f32 v[168:169], v[164:165], v[156:157] op_sel_hi:[1,0]
	v_add_f32_dpp v48, v47, v46 quad_perm:[1,0,3,2] row_mask:0xf bank_mask:0xf bound_ctrl:1
	v_add_f32_dpp v52, v51, v50 quad_perm:[1,0,3,2] row_mask:0xf bank_mask:0xf bound_ctrl:1
	v_pk_mul_f32 v[170:171], v[164:165], v[156:157] op_sel:[0,1] op_sel_hi:[1,1]
	v_add_f32_dpp v48, v48, v48 quad_perm:[2,3,0,1] row_mask:0xf bank_mask:0xf bound_ctrl:1
	ds_write_b32 v0, v52 offset:59392
	v_pk_mul_f32 v[172:173], v[164:165], v[158:159] op_sel_hi:[1,0]
	v_pk_mul_f32 v[174:175], v[164:165], v[158:159] op_sel:[0,1] op_sel_hi:[1,1]
	v_add_f32_dpp v48, v48, v48 row_ror:4 row_mask:0xf bank_mask:0xf bound_ctrl:1
	v_pk_fma_f32 v[168:169], v[16:17], v[148:149], v[168:169] op_sel_hi:[1,0,1]
	v_pk_fma_f32 v[170:171], v[18:19], v[148:149], v[170:171] op_sel:[0,1,0] op_sel_hi:[1,1,1]
	v_add_f32_dpp v48, v48, v48 row_ror:8 row_mask:0xf bank_mask:0xf bound_ctrl:1
	v_pk_fma_f32 v[172:173], v[20:21], v[150:151], v[172:173] op_sel_hi:[1,0,1]
	v_pk_fma_f32 v[174:175], v[22:23], v[150:151], v[174:175] op_sel:[0,1,0] op_sel_hi:[1,1,1]
	v_mov_b32_dpp v49, v48 quad_perm:[1,0,3,2] row_mask:0xf bank_mask:0xf bound_ctrl:1
	v_pk_fma_f32 v[16:17], v[48:49], v[152:153], v[168:169] op_sel_hi:[1,0,1] neg_lo:[0,1,0] neg_hi:[0,1,0]
	v_pk_fma_f32 v[18:19], v[48:49], v[152:153], v[170:171] op_sel:[0,1,0] op_sel_hi:[1,1,1] neg_lo:[0,1,0] neg_hi:[0,1,0]
	v_pk_fma_f32 v[20:21], v[48:49], v[154:155], v[172:173] op_sel_hi:[1,0,1] neg_lo:[0,1,0] neg_hi:[0,1,0]
	v_pk_fma_f32 v[22:23], v[48:49], v[154:155], v[174:175] op_sel:[0,1,0] op_sel_hi:[1,1,1] neg_lo:[0,1,0] neg_hi:[0,1,0]
	ds_read_b128 v[144:147], v2 offset:19712
	ds_read_b64 v[164:165], v3 offset:15616
	ds_read_b128 v[156:159], v2 offset:11520
	ds_read_b128 v[148:151], v2 offset:7424
	ds_read_b128 v[152:155], v2 offset:23808
	s_waitcnt lgkmcnt(6)
	v_pk_mul_f32 v[46:47], v[16:17], v[24:25] op_sel_hi:[1,0]
	v_pk_mul_f32 v[50:51], v[16:17], v[160:161] op_sel_hi:[1,0]
	v_pk_fma_f32 v[46:47], v[18:19], v[24:25], v[46:47] op_sel:[0,1,0] op_sel_hi:[1,1,1]
	v_pk_fma_f32 v[50:51], v[18:19], v[160:161], v[50:51] op_sel:[0,1,0] op_sel_hi:[1,1,1]
	v_pk_fma_f32 v[46:47], v[20:21], v[26:27], v[46:47] op_sel_hi:[1,0,1]
	v_pk_fma_f32 v[50:51], v[20:21], v[162:163], v[50:51] op_sel_hi:[1,0,1]
	v_pk_fma_f32 v[46:47], v[22:23], v[26:27], v[46:47] op_sel:[0,1,0] op_sel_hi:[1,1,1]
	v_pk_fma_f32 v[50:51], v[22:23], v[162:163], v[50:51] op_sel:[0,1,0] op_sel_hi:[1,1,1]
	ds_read_b128 v[160:163], v2 offset:3328
	v_pk_mul_f32 v[168:169], v[44:45], v[36:37] op_sel_hi:[1,0]
	v_add_f32_dpp v48, v47, v46 quad_perm:[1,0,3,2] row_mask:0xf bank_mask:0xf bound_ctrl:1
	v_add_f32_dpp v52, v51, v50 quad_perm:[1,0,3,2] row_mask:0xf bank_mask:0xf bound_ctrl:1
	v_pk_mul_f32 v[170:171], v[44:45], v[36:37] op_sel:[0,1] op_sel_hi:[1,1]
	v_add_f32_dpp v48, v48, v48 quad_perm:[2,3,0,1] row_mask:0xf bank_mask:0xf bound_ctrl:1
	ds_write_b32 v0, v52 offset:60416
	v_pk_mul_f32 v[172:173], v[44:45], v[38:39] op_sel_hi:[1,0]
	v_pk_mul_f32 v[174:175], v[44:45], v[38:39] op_sel:[0,1] op_sel_hi:[1,1]
	v_add_f32_dpp v48, v48, v48 row_ror:4 row_mask:0xf bank_mask:0xf bound_ctrl:1
	v_pk_fma_f32 v[168:169], v[16:17], v[28:29], v[168:169] op_sel_hi:[1,0,1]
	v_pk_fma_f32 v[170:171], v[18:19], v[28:29], v[170:171] op_sel:[0,1,0] op_sel_hi:[1,1,1]
	v_add_f32_dpp v48, v48, v48 row_ror:8 row_mask:0xf bank_mask:0xf bound_ctrl:1
	v_pk_fma_f32 v[172:173], v[20:21], v[30:31], v[172:173] op_sel_hi:[1,0,1]
	v_pk_fma_f32 v[174:175], v[22:23], v[30:31], v[174:175] op_sel:[0,1,0] op_sel_hi:[1,1,1]
	v_mov_b32_dpp v49, v48 quad_perm:[1,0,3,2] row_mask:0xf bank_mask:0xf bound_ctrl:1
	v_pk_fma_f32 v[16:17], v[48:49], v[32:33], v[168:169] op_sel_hi:[1,0,1] neg_lo:[0,1,0] neg_hi:[0,1,0]
	v_pk_fma_f32 v[18:19], v[48:49], v[32:33], v[170:171] op_sel:[0,1,0] op_sel_hi:[1,1,1] neg_lo:[0,1,0] neg_hi:[0,1,0]
	v_pk_fma_f32 v[20:21], v[48:49], v[34:35], v[172:173] op_sel_hi:[1,0,1] neg_lo:[0,1,0] neg_hi:[0,1,0]
	v_pk_fma_f32 v[22:23], v[48:49], v[34:35], v[174:175] op_sel:[0,1,0] op_sel_hi:[1,1,1] neg_lo:[0,1,0] neg_hi:[0,1,0]
	ds_read_b128 v[24:27], v2 offset:19968
	ds_read_b64 v[44:45], v3 offset:15872
	ds_read_b128 v[36:39], v2 offset:11776
	ds_read_b128 v[28:31], v2 offset:7680
	ds_read_b128 v[32:35], v2 offset:24064
	s_waitcnt lgkmcnt(6)
	v_pk_mul_f32 v[46:47], v[16:17], v[144:145] op_sel_hi:[1,0]
	v_pk_mul_f32 v[50:51], v[16:17], v[40:41] op_sel_hi:[1,0]
	v_pk_fma_f32 v[46:47], v[18:19], v[144:145], v[46:47] op_sel:[0,1,0] op_sel_hi:[1,1,1]
	v_pk_fma_f32 v[50:51], v[18:19], v[40:41], v[50:51] op_sel:[0,1,0] op_sel_hi:[1,1,1]
	v_pk_fma_f32 v[46:47], v[20:21], v[146:147], v[46:47] op_sel_hi:[1,0,1]
	v_pk_fma_f32 v[50:51], v[20:21], v[42:43], v[50:51] op_sel_hi:[1,0,1]
	v_pk_fma_f32 v[46:47], v[22:23], v[146:147], v[46:47] op_sel:[0,1,0] op_sel_hi:[1,1,1]
	v_pk_fma_f32 v[50:51], v[22:23], v[42:43], v[50:51] op_sel:[0,1,0] op_sel_hi:[1,1,1]
	ds_read_b128 v[40:43], v2 offset:3584
	v_pk_mul_f32 v[168:169], v[164:165], v[156:157] op_sel_hi:[1,0]
	v_add_f32_dpp v48, v47, v46 quad_perm:[1,0,3,2] row_mask:0xf bank_mask:0xf bound_ctrl:1
	v_add_f32_dpp v52, v51, v50 quad_perm:[1,0,3,2] row_mask:0xf bank_mask:0xf bound_ctrl:1
	v_pk_mul_f32 v[170:171], v[164:165], v[156:157] op_sel:[0,1] op_sel_hi:[1,1]
	v_add_f32_dpp v48, v48, v48 quad_perm:[2,3,0,1] row_mask:0xf bank_mask:0xf bound_ctrl:1
	ds_write_b32 v0, v52 offset:61440
	v_pk_mul_f32 v[172:173], v[164:165], v[158:159] op_sel_hi:[1,0]
	v_pk_mul_f32 v[174:175], v[164:165], v[158:159] op_sel:[0,1] op_sel_hi:[1,1]
	v_add_f32_dpp v48, v48, v48 row_ror:4 row_mask:0xf bank_mask:0xf bound_ctrl:1
	v_pk_fma_f32 v[168:169], v[16:17], v[148:149], v[168:169] op_sel_hi:[1,0,1]
	v_pk_fma_f32 v[170:171], v[18:19], v[148:149], v[170:171] op_sel:[0,1,0] op_sel_hi:[1,1,1]
	v_add_f32_dpp v48, v48, v48 row_ror:8 row_mask:0xf bank_mask:0xf bound_ctrl:1
	v_pk_fma_f32 v[172:173], v[20:21], v[150:151], v[172:173] op_sel_hi:[1,0,1]
	v_pk_fma_f32 v[174:175], v[22:23], v[150:151], v[174:175] op_sel:[0,1,0] op_sel_hi:[1,1,1]
	v_mov_b32_dpp v49, v48 quad_perm:[1,0,3,2] row_mask:0xf bank_mask:0xf bound_ctrl:1
	v_pk_fma_f32 v[16:17], v[48:49], v[152:153], v[168:169] op_sel_hi:[1,0,1] neg_lo:[0,1,0] neg_hi:[0,1,0]
	v_pk_fma_f32 v[18:19], v[48:49], v[152:153], v[170:171] op_sel:[0,1,0] op_sel_hi:[1,1,1] neg_lo:[0,1,0] neg_hi:[0,1,0]
	v_pk_fma_f32 v[20:21], v[48:49], v[154:155], v[172:173] op_sel_hi:[1,0,1] neg_lo:[0,1,0] neg_hi:[0,1,0]
	v_pk_fma_f32 v[22:23], v[48:49], v[154:155], v[174:175] op_sel:[0,1,0] op_sel_hi:[1,1,1] neg_lo:[0,1,0] neg_hi:[0,1,0]
	ds_read_b128 v[144:147], v2 offset:20224
	ds_read_b64 v[164:165], v3 offset:16128
	ds_read_b128 v[156:159], v2 offset:12032
	ds_read_b128 v[148:151], v2 offset:7936
	ds_read_b128 v[152:155], v2 offset:24320
	s_waitcnt lgkmcnt(6)
	v_pk_mul_f32 v[46:47], v[16:17], v[24:25] op_sel_hi:[1,0]
	v_pk_mul_f32 v[50:51], v[16:17], v[160:161] op_sel_hi:[1,0]
	v_pk_fma_f32 v[46:47], v[18:19], v[24:25], v[46:47] op_sel:[0,1,0] op_sel_hi:[1,1,1]
	v_pk_fma_f32 v[50:51], v[18:19], v[160:161], v[50:51] op_sel:[0,1,0] op_sel_hi:[1,1,1]
	v_pk_fma_f32 v[46:47], v[20:21], v[26:27], v[46:47] op_sel_hi:[1,0,1]
	v_pk_fma_f32 v[50:51], v[20:21], v[162:163], v[50:51] op_sel_hi:[1,0,1]
	v_pk_fma_f32 v[46:47], v[22:23], v[26:27], v[46:47] op_sel:[0,1,0] op_sel_hi:[1,1,1]
	v_pk_fma_f32 v[50:51], v[22:23], v[162:163], v[50:51] op_sel:[0,1,0] op_sel_hi:[1,1,1]
	ds_read_b128 v[160:163], v2 offset:3840
	v_pk_mul_f32 v[168:169], v[44:45], v[36:37] op_sel_hi:[1,0]
	v_add_f32_dpp v48, v47, v46 quad_perm:[1,0,3,2] row_mask:0xf bank_mask:0xf bound_ctrl:1
	v_add_f32_dpp v52, v51, v50 quad_perm:[1,0,3,2] row_mask:0xf bank_mask:0xf bound_ctrl:1
	v_pk_mul_f32 v[170:171], v[44:45], v[36:37] op_sel:[0,1] op_sel_hi:[1,1]
	v_add_f32_dpp v48, v48, v48 quad_perm:[2,3,0,1] row_mask:0xf bank_mask:0xf bound_ctrl:1
	ds_write_b32 v0, v52 offset:62464
	v_pk_mul_f32 v[172:173], v[44:45], v[38:39] op_sel_hi:[1,0]
	v_pk_mul_f32 v[174:175], v[44:45], v[38:39] op_sel:[0,1] op_sel_hi:[1,1]
	v_add_f32_dpp v48, v48, v48 row_ror:4 row_mask:0xf bank_mask:0xf bound_ctrl:1
	v_pk_fma_f32 v[168:169], v[16:17], v[28:29], v[168:169] op_sel_hi:[1,0,1]
	v_pk_fma_f32 v[170:171], v[18:19], v[28:29], v[170:171] op_sel:[0,1,0] op_sel_hi:[1,1,1]
	v_add_f32_dpp v48, v48, v48 row_ror:8 row_mask:0xf bank_mask:0xf bound_ctrl:1
	v_pk_fma_f32 v[172:173], v[20:21], v[30:31], v[172:173] op_sel_hi:[1,0,1]
	v_pk_fma_f32 v[174:175], v[22:23], v[30:31], v[174:175] op_sel:[0,1,0] op_sel_hi:[1,1,1]
	v_mov_b32_dpp v49, v48 quad_perm:[1,0,3,2] row_mask:0xf bank_mask:0xf bound_ctrl:1
	v_pk_fma_f32 v[16:17], v[48:49], v[32:33], v[168:169] op_sel_hi:[1,0,1] neg_lo:[0,1,0] neg_hi:[0,1,0]
	v_pk_fma_f32 v[18:19], v[48:49], v[32:33], v[170:171] op_sel:[0,1,0] op_sel_hi:[1,1,1] neg_lo:[0,1,0] neg_hi:[0,1,0]
	v_pk_fma_f32 v[20:21], v[48:49], v[34:35], v[172:173] op_sel_hi:[1,0,1] neg_lo:[0,1,0] neg_hi:[0,1,0]
	v_pk_fma_f32 v[22:23], v[48:49], v[34:35], v[174:175] op_sel:[0,1,0] op_sel_hi:[1,1,1] neg_lo:[0,1,0] neg_hi:[0,1,0]
	s_waitcnt lgkmcnt(1)
	v_pk_mul_f32 v[46:47], v[16:17], v[144:145] op_sel_hi:[1,0]
	v_pk_mul_f32 v[50:51], v[16:17], v[40:41] op_sel_hi:[1,0]
	v_pk_fma_f32 v[46:47], v[18:19], v[144:145], v[46:47] op_sel:[0,1,0] op_sel_hi:[1,1,1]
	v_pk_fma_f32 v[50:51], v[18:19], v[40:41], v[50:51] op_sel:[0,1,0] op_sel_hi:[1,1,1]
	v_pk_fma_f32 v[46:47], v[20:21], v[146:147], v[46:47] op_sel_hi:[1,0,1]
	v_pk_fma_f32 v[50:51], v[20:21], v[42:43], v[50:51] op_sel_hi:[1,0,1]
	v_pk_fma_f32 v[46:47], v[22:23], v[146:147], v[46:47] op_sel:[0,1,0] op_sel_hi:[1,1,1]
	v_pk_fma_f32 v[50:51], v[22:23], v[42:43], v[50:51] op_sel:[0,1,0] op_sel_hi:[1,1,1]
	v_pk_mul_f32 v[168:169], v[164:165], v[156:157] op_sel_hi:[1,0]
	v_add_f32_dpp v48, v47, v46 quad_perm:[1,0,3,2] row_mask:0xf bank_mask:0xf bound_ctrl:1
	v_add_f32_dpp v52, v51, v50 quad_perm:[1,0,3,2] row_mask:0xf bank_mask:0xf bound_ctrl:1
	v_pk_mul_f32 v[170:171], v[164:165], v[156:157] op_sel:[0,1] op_sel_hi:[1,1]
	v_add_f32_dpp v48, v48, v48 quad_perm:[2,3,0,1] row_mask:0xf bank_mask:0xf bound_ctrl:1
	ds_write_b32 v0, v52 offset:63488
	v_pk_mul_f32 v[172:173], v[164:165], v[158:159] op_sel_hi:[1,0]
	v_pk_mul_f32 v[174:175], v[164:165], v[158:159] op_sel:[0,1] op_sel_hi:[1,1]
	v_add_f32_dpp v48, v48, v48 row_ror:4 row_mask:0xf bank_mask:0xf bound_ctrl:1
	v_pk_fma_f32 v[168:169], v[16:17], v[148:149], v[168:169] op_sel_hi:[1,0,1]
	v_pk_fma_f32 v[170:171], v[18:19], v[148:149], v[170:171] op_sel:[0,1,0] op_sel_hi:[1,1,1]
	v_add_f32_dpp v48, v48, v48 row_ror:8 row_mask:0xf bank_mask:0xf bound_ctrl:1
	v_pk_fma_f32 v[172:173], v[20:21], v[150:151], v[172:173] op_sel_hi:[1,0,1]
	v_pk_fma_f32 v[174:175], v[22:23], v[150:151], v[174:175] op_sel:[0,1,0] op_sel_hi:[1,1,1]
	v_mov_b32_dpp v49, v48 quad_perm:[1,0,3,2] row_mask:0xf bank_mask:0xf bound_ctrl:1
	v_pk_fma_f32 v[16:17], v[48:49], v[152:153], v[168:169] op_sel_hi:[1,0,1] neg_lo:[0,1,0] neg_hi:[0,1,0]
	v_pk_fma_f32 v[18:19], v[48:49], v[152:153], v[170:171] op_sel:[0,1,0] op_sel_hi:[1,1,1] neg_lo:[0,1,0] neg_hi:[0,1,0]
	v_pk_fma_f32 v[20:21], v[48:49], v[154:155], v[172:173] op_sel_hi:[1,0,1] neg_lo:[0,1,0] neg_hi:[0,1,0]
	v_pk_fma_f32 v[22:23], v[48:49], v[154:155], v[174:175] op_sel:[0,1,0] op_sel_hi:[1,1,1] neg_lo:[0,1,0] neg_hi:[0,1,0]
	v_pk_mul_f32 v[50:51], v[16:17], v[160:161] op_sel_hi:[1,0]
	v_pk_fma_f32 v[50:51], v[18:19], v[160:161], v[50:51] op_sel:[0,1,0] op_sel_hi:[1,1,1]
	v_pk_fma_f32 v[50:51], v[20:21], v[162:163], v[50:51] op_sel_hi:[1,0,1]
	v_pk_fma_f32 v[50:51], v[22:23], v[162:163], v[50:51] op_sel:[0,1,0] op_sel_hi:[1,1,1]
	s_nop 1
	v_add_f32_dpp v52, v51, v50 quad_perm:[1,0,3,2] row_mask:0xf bank_mask:0xf bound_ctrl:1
	ds_write_b32 v0, v52 offset:64512

.LBB0_550:
	s_andn2_b64 vcc, exec, s[4:5]
	s_cbranch_vccnz .LBB0_555
	v_lshlrev_b32_e32 v2, 16, v96
	v_and_b32_e32 v3, 0xffff0000, v96
	v_lshlrev_b32_e32 v32, 16, v97
	v_and_b32_e32 v33, 0xffff0000, v97
	v_pk_mul_f32 v[40:41], v[4:5], v[2:3]
	v_pk_mul_f32 v[42:43], v[6:7], v[32:33]
	v_pk_mul_f32 v[36:37], v[40:41], v[40:41]
	v_pk_mul_f32 v[34:35], v[42:43], v[42:43]
	v_lshlrev_b32_e32 v44, 16, v102
	v_pk_mov_b32 v[38:39], v[36:37], v[34:35] op_sel:[1,0]
	v_mov_b32_e32 v37, v35
	v_pk_add_f32 v[34:35], v[38:39], v[36:37]
	v_and_b32_e32 v45, 0xffff0000, v102
	v_lshlrev_b32_e32 v46, 16, v103
	v_and_b32_e32 v47, 0xffff0000, v103
	v_add_f32_e32 v0, v34, v35
	v_pk_add_f32 v[34:35], v[46:47], -1.0 op_sel_hi:[1,0]
	v_pk_add_f32 v[36:37], v[44:45], -1.0 op_sel_hi:[1,0]
	v_add_f32_dpp v0, v0, v0 quad_perm:[1,0,3,2] row_mask:0xf bank_mask:0xf bound_ctrl:1
	v_pk_fma_f32 v[36:37], v[8:9], v[36:37], 1.0 op_sel_hi:[1,1,0]
	v_pk_fma_f32 v[34:35], v[10:11], v[34:35], 1.0 op_sel_hi:[1,1,0]
	v_add_f32_dpp v0, v0, v0 quad_perm:[2,3,0,1] row_mask:0xf bank_mask:0xf bound_ctrl:1
	v_lshlrev_b32_e32 v24, 16, v94
	v_and_b32_e32 v25, 0xffff0000, v94
	v_add_f32_dpp v0, v0, v0 row_half_mirror row_mask:0xf bank_mask:0xf bound_ctrl:1
	v_pk_mul_f32 v[34:35], v[34:35], v[32:33]
	v_pk_mul_f32 v[32:33], v[36:37], v[2:3]
	v_lshlrev_b32_e32 v26, 16, v95
	v_and_b32_e32 v27, 0xffff0000, v95
	v_add_f32_dpp v0, v0, v0 row_mirror row_mask:0xf bank_mask:0xf bound_ctrl:1
	v_pk_mul_f32 v[2:3], v[32:33], v[24:25]
	v_lshlrev_b32_e32 v49, 16, v100
	v_max_f32_e32 v0, 0x179abe15, v0
	v_pk_mul_f32 v[36:37], v[34:35], v[26:27]
	v_pk_mul_f32 v[2:3], v[12:13], v[2:3]
	v_and_b32_e32 v50, 0xffff0000, v100
	v_rsq_f32_e32 v48, v0
	v_pk_mul_f32 v[36:37], v[14:15], v[36:37]
	v_add_f32_e32 v0, v2, v3
	v_mul_f32_e32 v3, 0xbfb8aa3b, v49
	v_lshlrev_b32_e32 v51, 16, v101
	v_add_f32_e32 v2, v36, v37
	v_exp_f32_e32 v36, v3
	v_mul_f32_e32 v3, 0xbfb8aa3b, v50
	v_and_b32_e32 v52, 0xffff0000, v101
	v_exp_f32_e32 v37, v3
	v_mul_f32_e32 v3, 0xbfb8aa3b, v51
	v_add_f32_e32 v0, v0, v2
	v_exp_f32_e32 v38, v3
	v_mul_f32_e32 v3, 0xbfb8aa3b, v52
	v_add_f32_dpp v0, v0, v0 quad_perm:[1,0,3,2] row_mask:0xf bank_mask:0xf bound_ctrl:1
	v_exp_f32_e32 v39, v3
	s_xor_b32 s4, s93, 1
	v_add_f32_dpp v0, v0, v0 quad_perm:[2,3,0,1] row_mask:0xf bank_mask:0xf bound_ctrl:1
	s_mulk_i32 s4, 0x6000
	v_pk_mul_f32 v[42:43], v[42:43], v[48:49] op_sel_hi:[1,0]
	v_add_f32_dpp v0, v0, v0 row_half_mirror row_mask:0xf bank_mask:0xf bound_ctrl:1
	v_pk_mul_f32 v[40:41], v[40:41], v[48:49] op_sel_hi:[1,0]
	v_add_u32_e32 v3, s4, v69
	v_lshlrev_b32_e32 v28, 16, v98
	v_and_b32_e32 v29, 0xffff0000, v98
	v_lshlrev_b32_e32 v30, 16, v99
	v_and_b32_e32 v31, 0xffff0000, v99
	v_mov_b32_dpp v2, v0 row_mirror row_mask:0xf bank_mask:0xf bound_ctrl:1
	ds_write_b128 v3, v[24:27]
	ds_write_b128 v3, v[36:39] offset:4096
	ds_write_b128 v3, v[32:35] offset:8192
	ds_write_b128 v3, v[28:31] offset:12288
	v_add_u32_e32 v197, 0x1d000, v3
	ds_write2_b32 v197, v29, v28 offset1:1
	ds_write2_b32 v197, v31, v30 offset0:2 offset1:3
	ds_write_b128 v3, v[40:43] offset:16384
	v_pk_mul_f32 v[26:27], v[42:43], v[46:47]
	v_pk_mul_f32 v[24:25], v[40:41], v[44:45]
	ds_write_b128 v3, v[24:27] offset:20480
	s_and_saveexec_b64 s[4:5], s[2:3]
	s_cbranch_execz .LBB0_553
	v_add_u32_e32 v24, s91, v142
	v_ashrrev_i32_e32 v25, 31, v24
	v_lshlrev_b64 v[24:25], 6, v[24:25]
	v_lshl_add_u64 v[24:25], s[52:53], 0, v[24:25]
	v_add_f32_e32 v0, v0, v2
	global_store_dword v[24:25], v0, off
